# P8: half of the 2-tile workgroups (cid bit3) start 13us late so epilogue HBM bursts interleave with the other half's mainloop
# speedup vs baseline: 1.0297x; 1.0130x over previous
.LBB0_1115:
	v_readlane_b32 s0, v246, 4
	v_readlane_b32 s1, v246, 5
	s_cmp_lt_i32 s0, 9
	s_cselect_b64 s[0:1], -1, 0
	s_and_b64 s[2:3], s[0:1], s[2:3]
	s_andn2_b64 vcc, exec, s[2:3]
	s_cbranch_vccnz .LBB0_1150
	s_cmp_lt_u32 s30, 16
	s_cbranch_scc1 .Lstg8_done
	s_bitcmp1_b32 s30, 3
	s_cbranch_scc0 .Lstg8_done
	s_sleep 127
	s_sleep 127
	s_sleep 127
	s_sleep 50
.Lstg8_done:
	s_add_u32 s2, s22, 0x13aa4000
	s_addc_u32 s3, s23, 0
	s_add_u32 s6, s22, 0xa80000
	s_addc_u32 s7, s23, 0
	s_cmpk_lt_i32 s30, 0x210
	s_cselect_b64 s[4:5], -1, 0
	s_cmpk_gt_i32 s30, 0x20f
	v_readfirstlane_b32 s33, v202
	s_cbranch_scc1 .LBB0_1118
	s_ashr_i32 s8, s30, 31
	s_lshr_b32 s8, s8, 29
	s_add_i32 s8, s30, s8
	s_ashr_i32 s9, s8, 3
	s_and_b32 s8, s8, -8
	s_sub_i32 s8, s30, s8
	s_cmp_lt_i32 s8, 0
	s_movk_i32 s10, 0x43
	s_cselect_b32 s10, s10, 0x42
	s_mul_i32 s8, s8, s10
	s_add_i32 s8, s8, s9
	s_ashr_i32 s9, s8, 31
	s_lshr_b32 s9, s9, 27
	s_add_i32 s9, s8, s9
	s_ashr_i32 s9, s9, 5
	s_lshl_b32 s10, s9, 3
	s_sub_i32 s11, 0x84, s10
	s_lshl_b32 s9, s9, 5
	s_min_u32 s11, s11, 8
	s_sub_i32 s12, s8, s9
	s_sext_i32_i8 s8, s12
	s_waitcnt lgkmcnt(0)
	v_cvt_f32_ubyte0_e32 v1, s11
	v_cvt_f32_i32_e32 v0, s8
	v_rcp_iflag_f32_e32 v2, v1
	s_ashr_i32 s8, s8, 30
	s_or_b32 s13, s8, 1
	v_mul_f32_e32 v2, v0, v2
	v_trunc_f32_e32 v2, v2
	v_fma_f32 v0, -v2, v1, v0
	v_cvt_i32_f32_e32 v2, v2
	v_cmp_ge_f32_e64 s[8:9], |v0|, v1
	s_and_b64 s[8:9], s[8:9], exec
	s_cselect_b32 s8, s13, 0
	v_readfirstlane_b32 s9, v2
	s_add_i32 s8, s9, s8
	s_mul_i32 s9, s8, s11
	s_sub_i32 s9, s12, s9
	s_sext_i32_i8 s9, s9
	s_add_i32 s18, s10, s9
	s_ashr_i32 s19, s18, 31
	s_lshl_b64 s[10:11], s[18:19], 18
	s_add_u32 s24, s2, s10
	s_sext_i32_i8 s63, s8
	s_addc_u32 s25, s3, s11
	s_bfe_i64 s[8:9], s[8:9], 0x80000
	s_lshl_b64 s[8:9], s[8:9], 18
	s_add_u32 s26, s6, s8
	s_addc_u32 s27, s7, s9
	s_andn2_b64 vcc, exec, s[4:5]
	s_cbranch_vccz .LBB0_1119
	s_branch .LBB0_1150
